# grid barrier: non-leader workgroups poll TOPGEN directly (one hop fewer per seam); attention epilogue stores widened to dwordx4 via permlane32 swap; plus earlier rel-bias batching and deferred ticket
# speedup vs baseline: 1.0491x; 1.0074x over previous
; __device__ __forceinline__ unsigned xb_ld(unsigned* p)              { return __hip_atomic_load(p, __ATOMIC_RELAXED, __HIP_MEMORY_SCOPE_AGENT); }
; __device__ __forceinline__ unsigned xb_add(unsigned* p, unsigned v) { return __hip_atomic_fetch_add(p, v, __ATOMIC_RELAXED, __HIP_MEMORY_SCOPE_AGENT); }
; #define XB_SPIN(cond, bar) do { unsigned _sp = 0; while (cond) { __builtin_amdgcn_s_sleep(1); \
;     if ((++_sp & 255u) == 0u) { if (xb_ld(&(bar)[XB_TMO])) break; if (_sp > XB_SPIN_CAP) { atomicAdd(&(bar)[XB_TMO], 1u); break; } } } } while (0)
; __device__ __forceinline__ void xcd_barrier(const XcdBarrier& b, bool leader_thread) {
;     ...
;         unsigned nloc = b.st[0], nx = b.st[1];
;         if (nloc == 0u) { xcd_barrier_complete(bar, b.x, nloc, nx); b.st[0] = nloc; b.st[1] = nx; }
;         const unsigned old = xb_add(&bar[XB_XSUB(b.x)], 1u);
;         const unsigned gen = old / nloc;
;         if (old + 1u == (gen + 1u) * nloc) {
;             __builtin_amdgcn_fence(__ATOMIC_RELEASE, "agent");
;             asm volatile("s_waitcnt vmcnt(0)" ::: "memory");
;             const unsigned og = xb_add(&bar[XB_TOP], 1u);
;             const unsigned tg = og / nx;
;             if (og + 1u == (tg + 1u) * nx) xb_add(&bar[XB_TOPGEN], 1u);
;             else XB_SPIN(xb_ld(&bar[XB_TOPGEN]) == tg, bar);
;             __builtin_amdgcn_fence(__ATOMIC_ACQUIRE, "agent");
;             xb_add(&bar[XB_XGEN(b.x)], 1u);
;             asm volatile("s_waitcnt vmcnt(0)" ::: "memory");
;         } else {
;             XB_SPIN(xb_ld(&bar[XB_XGEN(b.x)]) == gen, bar);
.LBB0_140:
	s_or_b64 exec, exec, s[4:5]
	v_cvt_f32_u32_e32 v5, v3
	s_waitcnt vmcnt(0)
	v_readfirstlane_b32 s2, v4
	v_sub_u32_e32 v4, 0, v3
	v_rcp_iflag_f32_e32 v5, v5
	v_add_u32_e32 v6, s2, v0
	v_mul_f32_e32 v5, 0x4f7ffffe, v5
	v_cvt_u32_f32_e32 v5, v5
	v_mul_lo_u32 v0, v4, v5
	v_mul_hi_u32 v0, v5, v0
	v_add_u32_e32 v0, v5, v0
	v_mul_hi_u32 v0, v6, v0
	v_mul_lo_u32 v4, v0, v3
	v_sub_u32_e32 v4, v6, v4
	v_add_u32_e32 v5, 1, v0
	v_cmp_ge_u32_e32 vcc, v4, v3
	s_nop 1
	v_cndmask_b32_e32 v0, v0, v5, vcc
	v_sub_u32_e32 v5, v4, v3
	v_cndmask_b32_e32 v4, v4, v5, vcc
	v_add_u32_e32 v5, 1, v0
	v_cmp_ge_u32_e32 vcc, v4, v3
	v_add_u32_e32 v4, 1, v6
	s_nop 0
	v_cndmask_b32_e32 v0, v0, v5, vcc
	v_mul_lo_u32 v5, v3, v0
	v_add_u32_e32 v3, v5, v3
	v_cmp_ne_u32_e32 vcc, v4, v3
	s_and_saveexec_b64 s[2:3], vcc
	s_xor_b64 s[4:5], exec, s[2:3]
	s_cbranch_execz .LBB0_154
	v_readlane_b32 s2, v252, 59
	v_readlane_b32 s3, v252, 60
	s_waitcnt lgkmcnt(0)
	s_nop 3
	global_load_dword v2, v1, s[2:3] sc1
	s_waitcnt vmcnt(0)
	v_cmp_eq_u32_e32 vcc, v2, v0
	s_and_saveexec_b64 s[6:7], vcc
	s_cbranch_execz .LBB0_153
	s_mov_b32 s2, 1
	s_mov_b64 s[8:9], 0
	s_branch .LBB0_144

; __device__ __forceinline__ unsigned xb_ld(unsigned* p)              { return __hip_atomic_load(p, __ATOMIC_RELAXED, __HIP_MEMORY_SCOPE_AGENT); }
; __device__ __forceinline__ unsigned xb_add(unsigned* p, unsigned v) { return __hip_atomic_fetch_add(p, v, __ATOMIC_RELAXED, __HIP_MEMORY_SCOPE_AGENT); }
; #define XB_SPIN(cond, bar) do { unsigned _sp = 0; while (cond) { __builtin_amdgcn_s_sleep(1); \
;     if ((++_sp & 255u) == 0u) { if (xb_ld(&(bar)[XB_TMO])) break; if (_sp > XB_SPIN_CAP) { atomicAdd(&(bar)[XB_TMO], 1u); break; } } } } while (0)
; __device__ __forceinline__ void xcd_barrier(const XcdBarrier& b, bool leader_thread) {
;     ...
;         unsigned nloc = b.st[0], nx = b.st[1];
;         if (nloc == 0u) { xcd_barrier_complete(bar, b.x, nloc, nx); b.st[0] = nloc; b.st[1] = nx; }
;         const unsigned old = xb_add(&bar[XB_XSUB(b.x)], 1u);
;         const unsigned gen = old / nloc;
;         if (old + 1u == (gen + 1u) * nloc) {
;             __builtin_amdgcn_fence(__ATOMIC_RELEASE, "agent");
;             asm volatile("s_waitcnt vmcnt(0)" ::: "memory");
;             const unsigned og = xb_add(&bar[XB_TOP], 1u);
;             const unsigned tg = og / nx;
;             if (og + 1u == (tg + 1u) * nx) xb_add(&bar[XB_TOPGEN], 1u);
;             else XB_SPIN(xb_ld(&bar[XB_TOPGEN]) == tg, bar);
;             __builtin_amdgcn_fence(__ATOMIC_ACQUIRE, "agent");
;             xb_add(&bar[XB_XGEN(b.x)], 1u);
;             asm volatile("s_waitcnt vmcnt(0)" ::: "memory");
;         } else {
;             XB_SPIN(xb_ld(&bar[XB_XGEN(b.x)]) == gen, bar);
.LBB0_324:
	s_or_b64 exec, exec, s[8:9]
	v_cvt_f32_u32_e32 v5, v3
	s_waitcnt vmcnt(0)
	v_readfirstlane_b32 s3, v4
	v_sub_u32_e32 v4, 0, v3
	v_rcp_iflag_f32_e32 v5, v5
	v_add_u32_e32 v6, s3, v0
	v_mul_f32_e32 v5, 0x4f7ffffe, v5
	v_cvt_u32_f32_e32 v5, v5
	v_mul_lo_u32 v0, v4, v5
	v_mul_hi_u32 v0, v5, v0
	v_add_u32_e32 v0, v5, v0
	v_mul_hi_u32 v0, v6, v0
	v_mul_lo_u32 v4, v0, v3
	v_sub_u32_e32 v4, v6, v4
	v_add_u32_e32 v5, 1, v0
	v_cmp_ge_u32_e32 vcc, v4, v3
	s_nop 1
	v_cndmask_b32_e32 v0, v0, v5, vcc
	v_sub_u32_e32 v5, v4, v3
	v_cndmask_b32_e32 v4, v4, v5, vcc
	v_add_u32_e32 v5, 1, v0
	v_cmp_ge_u32_e32 vcc, v4, v3
	v_add_u32_e32 v4, 1, v6
	s_nop 0
	v_cndmask_b32_e32 v0, v0, v5, vcc
	v_mul_lo_u32 v5, v3, v0
	v_add_u32_e32 v3, v5, v3
	v_cmp_ne_u32_e32 vcc, v4, v3
	s_and_saveexec_b64 s[8:9], vcc
	s_xor_b64 s[8:9], exec, s[8:9]
	s_cbranch_execz .LBB0_338
	v_readlane_b32 s6, v252, 59
	v_readlane_b32 s7, v252, 60
	s_waitcnt lgkmcnt(0)
	s_nop 3
	global_load_dword v2, v1, s[6:7] sc1
	s_waitcnt vmcnt(0)
	v_cmp_eq_u32_e32 vcc, v2, v0
	s_and_saveexec_b64 s[10:11], vcc
	s_cbranch_execz .LBB0_337
	s_mov_b32 s3, 1
	s_mov_b64 s[20:21], 0
	s_branch .LBB0_328

; __device__ __forceinline__ unsigned xb_ld(unsigned* p)              { return __hip_atomic_load(p, __ATOMIC_RELAXED, __HIP_MEMORY_SCOPE_AGENT); }
; __device__ __forceinline__ unsigned xb_add(unsigned* p, unsigned v) { return __hip_atomic_fetch_add(p, v, __ATOMIC_RELAXED, __HIP_MEMORY_SCOPE_AGENT); }
; #define XB_SPIN(cond, bar) do { unsigned _sp = 0; while (cond) { __builtin_amdgcn_s_sleep(1); \
;     if ((++_sp & 255u) == 0u) { if (xb_ld(&(bar)[XB_TMO])) break; if (_sp > XB_SPIN_CAP) { atomicAdd(&(bar)[XB_TMO], 1u); break; } } } } while (0)
; __device__ __forceinline__ void xcd_barrier(const XcdBarrier& b, bool leader_thread) {
;     ...
;         unsigned nloc = b.st[0], nx = b.st[1];
;         if (nloc == 0u) { xcd_barrier_complete(bar, b.x, nloc, nx); b.st[0] = nloc; b.st[1] = nx; }
;         const unsigned old = xb_add(&bar[XB_XSUB(b.x)], 1u);
;         const unsigned gen = old / nloc;
;         if (old + 1u == (gen + 1u) * nloc) {
;             __builtin_amdgcn_fence(__ATOMIC_RELEASE, "agent");
;             asm volatile("s_waitcnt vmcnt(0)" ::: "memory");
;             const unsigned og = xb_add(&bar[XB_TOP], 1u);
;             const unsigned tg = og / nx;
;             if (og + 1u == (tg + 1u) * nx) xb_add(&bar[XB_TOPGEN], 1u);
;             else XB_SPIN(xb_ld(&bar[XB_TOPGEN]) == tg, bar);
;             __builtin_amdgcn_fence(__ATOMIC_ACQUIRE, "agent");
;             xb_add(&bar[XB_XGEN(b.x)], 1u);
;             asm volatile("s_waitcnt vmcnt(0)" ::: "memory");
;         } else {
;             XB_SPIN(xb_ld(&bar[XB_XGEN(b.x)]) == gen, bar);
.LBB0_548:
	s_or_b64 exec, exec, s[6:7]
	v_cvt_f32_u32_e32 v5, v3
	s_waitcnt vmcnt(0)
	v_readfirstlane_b32 s3, v4
	v_sub_u32_e32 v4, 0, v3
	v_rcp_iflag_f32_e32 v5, v5
	v_add_u32_e32 v6, s3, v0
	v_mul_f32_e32 v5, 0x4f7ffffe, v5
	v_cvt_u32_f32_e32 v5, v5
	v_mul_lo_u32 v0, v4, v5
	v_mul_hi_u32 v0, v5, v0
	v_add_u32_e32 v0, v5, v0
	v_mul_hi_u32 v0, v6, v0
	v_mul_lo_u32 v4, v0, v3
	v_sub_u32_e32 v4, v6, v4
	v_add_u32_e32 v5, 1, v0
	v_cmp_ge_u32_e32 vcc, v4, v3
	s_nop 1
	v_cndmask_b32_e32 v0, v0, v5, vcc
	v_sub_u32_e32 v5, v4, v3
	v_cndmask_b32_e32 v4, v4, v5, vcc
	v_add_u32_e32 v5, 1, v0
	v_cmp_ge_u32_e32 vcc, v4, v3
	v_add_u32_e32 v4, 1, v6
	s_nop 0
	v_cndmask_b32_e32 v0, v0, v5, vcc
	v_mul_lo_u32 v5, v3, v0
	v_add_u32_e32 v3, v5, v3
	v_cmp_ne_u32_e32 vcc, v4, v3
	s_and_saveexec_b64 s[6:7], vcc
	s_xor_b64 s[6:7], exec, s[6:7]
	s_cbranch_execz .LBB0_562
	v_readlane_b32 s10, v252, 59
	v_readlane_b32 s11, v252, 60
	s_waitcnt lgkmcnt(0)
	s_nop 3
	global_load_dword v2, v1, s[10:11] sc1
	s_waitcnt vmcnt(0)
	v_cmp_eq_u32_e32 vcc, v2, v0
	s_and_saveexec_b64 s[10:11], vcc
	s_cbranch_execz .LBB0_561
	s_mov_b32 s3, 1
	s_mov_b64 s[20:21], 0
	s_branch .LBB0_552

; __device__ __forceinline__ unsigned pk2(float lo, float hi) { f32x2 v = {lo, hi}; bf16x2_t b = __builtin_convertvector(v, bf16x2_t); return __builtin_bit_cast(unsigned, b); }
; __device__ __forceinline__ float hsum(float m) { auto rr = __builtin_amdgcn_permlane32_swap(__float_as_uint(m), __float_as_uint(m), false, false); return __uint_as_float(rr[0]) + __uint_as_float(rr[1]); }
; template <int TYPE> __device__ __forceinline__ int unit(const P& p, LAS unsigned char* lds, int b, int h, int qb, int wave0, bool pre, unsigned nx, int G,
;         u32x4& kA, u32x4& vA, u32x4& k2A, float& cbA, u32x4& kB, u32x4& vB, u32x4& k2B, float& cbB) {
;     ...
;     const float inv = __builtin_amdgcn_rcpf(hsum(l_run));
;     bf16* yrow = Yp + (rowbase + 256 * qb + 32 * w + r32) * 512 + h * 64 + 4 * hi;
; #pragma unroll
;     for (int g = 0; g < 4; ++g) {
;         u32x2 w0, w1; w0.x = pk2(o0[4 * g] * inv, o0[4 * g + 1] * inv); w0.y = pk2(o0[4 * g + 2] * inv, o0[4 * g + 3] * inv);
;         w1.x = pk2(o1[4 * g] * inv, o1[4 * g + 1] * inv); w1.y = pk2(o1[4 * g + 2] * inv, o1[4 * g + 3] * inv);
;         *(u32x2*)(yrow + 8 * g) = w0; *(u32x2*)(yrow + 32 + 8 * g) = w1;
;     }
.LBB0_588:
	v_mov_b32_e32 v219, v1
	v_mul_f32_e32 v32, v0, v32
	v_mul_f32_e32 v33, v0, v33
	v_mul_f32_e32 v34, v0, v34
	v_mul_f32_e32 v35, v0, v35
	v_mul_f32_e32 v36, v0, v36
	v_mul_f32_e32 v37, v0, v37
	v_mul_f32_e32 v38, v0, v38
	v_mul_f32_e32 v39, v0, v39
	v_mul_f32_e32 v40, v0, v40
	v_mul_f32_e32 v41, v0, v41
	v_mul_f32_e32 v42, v0, v42
	v_mul_f32_e32 v43, v0, v43
	v_mul_f32_e32 v44, v0, v44
	v_mul_f32_e32 v45, v0, v45
	v_mul_f32_e32 v46, v0, v46
	v_mul_f32_e32 v47, v0, v47
	v_mul_f32_e32 v16, v0, v16
	v_mul_f32_e32 v17, v0, v17
	v_mul_f32_e32 v18, v0, v18
	v_mul_f32_e32 v19, v0, v19
	v_mul_f32_e32 v20, v0, v20
	v_mul_f32_e32 v21, v0, v21
	v_mul_f32_e32 v22, v0, v22
	v_mul_f32_e32 v23, v0, v23
	v_mul_f32_e32 v24, v0, v24
	v_mul_f32_e32 v25, v0, v25
	v_mul_f32_e32 v26, v0, v26
	v_mul_f32_e32 v27, v0, v27
	v_mul_f32_e32 v28, v0, v28
	v_mul_f32_e32 v29, v0, v29
	v_mul_f32_e32 v30, v0, v30
	v_mul_f32_e32 v31, v0, v31
	v_lshl_add_u64 v[14:15], v[218:219], 2, v[14:15]
	v_cvt_pk_bf16_f32 v32, v32, v33
	v_cvt_pk_bf16_f32 v33, v34, v35
	v_cvt_pk_bf16_f32 v34, v36, v37
	v_cvt_pk_bf16_f32 v35, v38, v39
	v_cvt_pk_bf16_f32 v36, v40, v41
	v_cvt_pk_bf16_f32 v37, v42, v43
	v_cvt_pk_bf16_f32 v38, v44, v45
	v_cvt_pk_bf16_f32 v39, v46, v47
	v_cvt_pk_bf16_f32 v16, v16, v17
	v_cvt_pk_bf16_f32 v17, v18, v19
	v_cvt_pk_bf16_f32 v18, v20, v21
	v_cvt_pk_bf16_f32 v19, v22, v23
	v_cvt_pk_bf16_f32 v20, v24, v25
	v_cvt_pk_bf16_f32 v21, v26, v27
	v_cvt_pk_bf16_f32 v22, v28, v29
	v_cvt_pk_bf16_f32 v23, v30, v31
	s_nop 1
	v_permlane32_swap_b32_e32 v32, v34
	v_permlane32_swap_b32_e32 v33, v35
	v_permlane32_swap_b32_e32 v36, v38
	v_permlane32_swap_b32_e32 v37, v39
	v_permlane32_swap_b32_e32 v16, v18
	v_permlane32_swap_b32_e32 v17, v19
	v_permlane32_swap_b32_e32 v20, v22
	v_permlane32_swap_b32_e32 v21, v23
	global_store_dwordx4 v[14:15], v[32:35], off
	global_store_dwordx4 v[14:15], v[36:39], off offset:32
	global_store_dwordx4 v[14:15], v[16:19], off offset:64
	global_store_dwordx4 v[14:15], v[20:23], off offset:96
	s_waitcnt vmcnt(11)
	v_mov_b64_e32 v[118:119], v[4:5]
	s_waitcnt vmcnt(10)
	v_mov_b64_e32 v[114:115], v[8:9]
	s_waitcnt vmcnt(6)
	v_mov_b64_e32 v[98:99], v[82:83]
	v_mov_b64_e32 v[106:107], v[86:87]
	v_mov_b64_e32 v[110:111], v[12:13]
	s_waitcnt vmcnt(5)
	v_mov_b64_e32 v[102:103], v[90:91]
	s_mov_b64 s[0:1], -1
	s_cmpk_lt_i32 s25, 0x600
	v_mov_b64_e32 v[116:117], v[2:3]
	v_mov_b64_e32 v[112:113], v[6:7]
	v_mov_b64_e32 v[96:97], v[80:81]
	v_mov_b64_e32 v[104:105], v[84:85]
	v_mov_b64_e32 v[108:109], v[10:11]
	v_mov_b64_e32 v[100:101], v[88:89]
	s_cbranch_scc0 .LBB0_731

; __device__ __forceinline__ unsigned xb_ld(unsigned* p)              { return __hip_atomic_load(p, __ATOMIC_RELAXED, __HIP_MEMORY_SCOPE_AGENT); }
; __device__ __forceinline__ unsigned xb_add(unsigned* p, unsigned v) { return __hip_atomic_fetch_add(p, v, __ATOMIC_RELAXED, __HIP_MEMORY_SCOPE_AGENT); }
; #define XB_SPIN(cond, bar) do { unsigned _sp = 0; while (cond) { __builtin_amdgcn_s_sleep(1); \
;     if ((++_sp & 255u) == 0u) { if (xb_ld(&(bar)[XB_TMO])) break; if (_sp > XB_SPIN_CAP) { atomicAdd(&(bar)[XB_TMO], 1u); break; } } } } while (0)
; __device__ __forceinline__ void xcd_barrier(const XcdBarrier& b, bool leader_thread) {
;     ...
;         unsigned nloc = b.st[0], nx = b.st[1];
;         if (nloc == 0u) { xcd_barrier_complete(bar, b.x, nloc, nx); b.st[0] = nloc; b.st[1] = nx; }
;         const unsigned old = xb_add(&bar[XB_XSUB(b.x)], 1u);
;         const unsigned gen = old / nloc;
;         if (old + 1u == (gen + 1u) * nloc) {
;             __builtin_amdgcn_fence(__ATOMIC_RELEASE, "agent");
;             asm volatile("s_waitcnt vmcnt(0)" ::: "memory");
;             const unsigned og = xb_add(&bar[XB_TOP], 1u);
;             const unsigned tg = og / nx;
;             if (og + 1u == (tg + 1u) * nx) xb_add(&bar[XB_TOPGEN], 1u);
;             else XB_SPIN(xb_ld(&bar[XB_TOPGEN]) == tg, bar);
;             __builtin_amdgcn_fence(__ATOMIC_ACQUIRE, "agent");
;             xb_add(&bar[XB_XGEN(b.x)], 1u);
;             asm volatile("s_waitcnt vmcnt(0)" ::: "memory");
;         } else {
;             XB_SPIN(xb_ld(&bar[XB_XGEN(b.x)]) == gen, bar);
.LBB0_763:
	s_or_b64 exec, exec, s[6:7]
	v_cvt_f32_u32_e32 v5, v3
	s_waitcnt vmcnt(0)
	v_readfirstlane_b32 s3, v4
	v_sub_u32_e32 v4, 0, v3
	v_rcp_iflag_f32_e32 v5, v5
	v_add_u32_e32 v6, s3, v0
	v_mul_f32_e32 v5, 0x4f7ffffe, v5
	v_cvt_u32_f32_e32 v5, v5
	v_mul_lo_u32 v0, v4, v5
	v_mul_hi_u32 v0, v5, v0
	v_add_u32_e32 v0, v5, v0
	v_mul_hi_u32 v0, v6, v0
	v_mul_lo_u32 v4, v0, v3
	v_sub_u32_e32 v4, v6, v4
	v_add_u32_e32 v5, 1, v0
	v_cmp_ge_u32_e32 vcc, v4, v3
	s_nop 1
	v_cndmask_b32_e32 v0, v0, v5, vcc
	v_sub_u32_e32 v5, v4, v3
	v_cndmask_b32_e32 v4, v4, v5, vcc
	v_add_u32_e32 v5, 1, v0
	v_cmp_ge_u32_e32 vcc, v4, v3
	v_add_u32_e32 v4, 1, v6
	s_nop 0
	v_cndmask_b32_e32 v0, v0, v5, vcc
	v_mul_lo_u32 v5, v3, v0
	v_add_u32_e32 v3, v5, v3
	v_cmp_ne_u32_e32 vcc, v4, v3
	s_and_saveexec_b64 s[6:7], vcc
	s_xor_b64 s[6:7], exec, s[6:7]
	s_cbranch_execz .LBB0_777
	v_readlane_b32 s8, v252, 59
	v_readlane_b32 s9, v252, 60
	s_waitcnt lgkmcnt(0)
	s_nop 3
	global_load_dword v2, v1, s[8:9] sc1
	s_waitcnt vmcnt(0)
	v_cmp_eq_u32_e32 vcc, v2, v0
	s_and_saveexec_b64 s[8:9], vcc
	s_cbranch_execz .LBB0_776
	s_mov_b32 s3, 1
	s_mov_b64 s[10:11], 0
	s_branch .LBB0_767
